# GEMM unit headers: removed conservative vmcnt(0) before the K loop (loop's own counted waits retire the staged tiles)
# speedup vs baseline: 1.0065x; 1.0065x over previous
; template <class Epi, class Sched, bool ALIGN_EPI = false, bool SP2 = false>
; __device__ __forceinline__ void gemm_phase(PG8_LAS unsigned char* lds, const Gemm g, const Sched& S, const Epi& E) {
;     ...
;     f32x4 acc[2][2][4][2];
; #pragma unroll
;     for (int a = 0; a < 2; ++a)
; #pragma unroll
;         for (int b = 0; b < 2; ++b)
; #pragma unroll
;             for (int m = 0; m < 4; ++m)
; #pragma unroll
;                 for (int n = 0; n < 2; ++n) acc[a][b][m][n] = (f32x4){0.f, 0.f, 0.f, 0.f};
;     ...
;     for (;;) {
;         const bool has_next = S.next(ui + 1, nxt);
;         const char* nA = has_next ? (const char*)g.A + (size_t)nxt.pm * tstepA : cA; const char* nB = has_next ? (const char*)g.Bt + (size_t)nxt.pn * tstep : cB;
;         for (int t = 0; t < nt; t += 2) {
;             const bool last = (t == nt - 2);
;             const char* a1 = cA + (size_t)(t + 1) * kstep;
;             const char* a2 = last ? nA : cA + (size_t)(t + 2) * kstep; const char* b2 = last ? nB : cB + (size_t)(t + 2) * kstep;
;             const char* a3 = a2 + kstep; const char* b3 = b2 + kstep;
.LBB0_714:
	v_mov_b32_e32 v127, 0
	s_andn2_b64 vcc, exec, s[72:73]
	v_mov_b32_e32 v126, v127
	v_mov_b32_e32 v125, v127
	v_mov_b32_e32 v124, v127
	v_mov_b32_e32 v123, v127
	v_mov_b32_e32 v122, v127
	v_mov_b32_e32 v121, v127
	v_mov_b32_e32 v120, v127
	v_mov_b32_e32 v111, v127
	v_mov_b32_e32 v110, v127
	v_mov_b32_e32 v109, v127
	v_mov_b32_e32 v108, v127
	v_mov_b32_e32 v107, v127
	v_mov_b32_e32 v106, v127
	v_mov_b32_e32 v105, v127
	v_mov_b32_e32 v104, v127
	v_mov_b32_e32 v95, v127
	v_mov_b32_e32 v94, v127
	v_mov_b32_e32 v93, v127
	v_mov_b32_e32 v92, v127
	v_mov_b32_e32 v91, v127
	v_mov_b32_e32 v90, v127
	v_mov_b32_e32 v89, v127
	v_mov_b32_e32 v88, v127
	v_mov_b32_e32 v79, v127
	s_waitcnt lgkmcnt(0)
	v_mov_b32_e32 v78, v127
	v_mov_b32_e32 v77, v127
	v_mov_b32_e32 v76, v127
	v_mov_b32_e32 v75, v127
	v_mov_b32_e32 v74, v127
	v_mov_b32_e32 v73, v127
	v_mov_b32_e32 v72, v127
	v_mov_b32_e32 v119, v127
	v_mov_b32_e32 v118, v127
	v_mov_b32_e32 v117, v127
	v_mov_b32_e32 v116, v127
	v_mov_b32_e32 v115, v127
	v_mov_b32_e32 v114, v127
	v_mov_b32_e32 v113, v127
	v_mov_b32_e32 v112, v127
	v_mov_b32_e32 v103, v127
	v_mov_b32_e32 v102, v127
	v_mov_b32_e32 v101, v127
	v_mov_b32_e32 v100, v127
	v_mov_b32_e32 v99, v127
	v_mov_b32_e32 v98, v127
	v_mov_b32_e32 v97, v127
	v_mov_b32_e32 v96, v127
	v_mov_b32_e32 v87, v127
	v_mov_b32_e32 v86, v127
	v_mov_b32_e32 v85, v127
	v_mov_b32_e32 v84, v127
	v_mov_b32_e32 v83, v127
	v_mov_b32_e32 v82, v127
	v_mov_b32_e32 v81, v127
	v_mov_b32_e32 v80, v127
	v_mov_b32_e32 v71, v127
	v_mov_b32_e32 v70, v127
	v_mov_b32_e32 v69, v127
	v_mov_b32_e32 v68, v127
	v_mov_b32_e32 v67, v127
	v_mov_b32_e32 v66, v127
	v_mov_b32_e32 v65, v127
	v_mov_b32_e32 v64, v127
	v_mov_b32_e32 v63, v127
	v_mov_b32_e32 v62, v127
	v_mov_b32_e32 v61, v127
	v_mov_b32_e32 v60, v127
	v_mov_b32_e32 v59, v127
	v_mov_b32_e32 v58, v127
	v_mov_b32_e32 v57, v127
	v_mov_b32_e32 v56, v127
	v_mov_b32_e32 v47, v127
	v_mov_b32_e32 v46, v127
	v_mov_b32_e32 v45, v127
	v_mov_b32_e32 v44, v127
	v_mov_b32_e32 v43, v127
	v_mov_b32_e32 v42, v127
	v_mov_b32_e32 v41, v127
	v_mov_b32_e32 v40, v127
	v_mov_b32_e32 v31, v127
	v_mov_b32_e32 v30, v127
	v_mov_b32_e32 v29, v127
	v_mov_b32_e32 v28, v127
	v_mov_b32_e32 v27, v127
	v_mov_b32_e32 v26, v127
	v_mov_b32_e32 v25, v127
	v_mov_b32_e32 v24, v127
	v_mov_b32_e32 v15, v127
	v_mov_b32_e32 v14, v127
	v_mov_b32_e32 v13, v127
	v_mov_b32_e32 v12, v127
	v_mov_b32_e32 v11, v127
	v_mov_b32_e32 v10, v127
	v_mov_b32_e32 v9, v127
	v_mov_b32_e32 v8, v127
	v_mov_b32_e32 v55, v127
	v_mov_b32_e32 v54, v127
	v_mov_b32_e32 v53, v127
	v_mov_b32_e32 v52, v127
	v_mov_b32_e32 v51, v127
	v_mov_b32_e32 v50, v127
	v_mov_b32_e32 v49, v127
	v_mov_b32_e32 v48, v127
	v_mov_b32_e32 v39, v127
	v_mov_b32_e32 v38, v127
	v_mov_b32_e32 v37, v127
	v_mov_b32_e32 v36, v127
	v_mov_b32_e32 v35, v127
	v_mov_b32_e32 v34, v127
	v_mov_b32_e32 v33, v127
	v_mov_b32_e32 v32, v127
	v_mov_b32_e32 v23, v127
	v_mov_b32_e32 v22, v127
	v_mov_b32_e32 v21, v127
	v_mov_b32_e32 v20, v127
	v_mov_b32_e32 v19, v127
	v_mov_b32_e32 v18, v127
	v_mov_b32_e32 v17, v127
	v_mov_b32_e32 v16, v127
	v_mov_b32_e32 v7, v127
	v_mov_b32_e32 v6, v127
	v_mov_b32_e32 v5, v127
	v_mov_b32_e32 v4, v127
	v_mov_b32_e32 v3, v127
	v_mov_b32_e32 v2, v127
	v_mov_b32_e32 v1, v127
	v_mov_b32_e32 v0, v127
	s_cbranch_vccnz .LBB0_717
	s_add_u32 s0, s46, 0x80
	s_addc_u32 s1, s47, 0
	s_add_u32 s20, s44, 0x100
	v_mov_b32_e32 v0, 0
	s_addc_u32 s21, s45, 0
	s_mov_b32 s28, 0
	v_mov_b32_e32 v1, v0
	v_mov_b32_e32 v2, v0
	v_mov_b32_e32 v3, v0
	v_mov_b32_e32 v4, v0
	v_mov_b32_e32 v5, v0
	v_mov_b32_e32 v6, v0
	v_mov_b32_e32 v7, v0
	v_mov_b32_e32 v16, v0
	v_mov_b32_e32 v17, v0
	v_mov_b32_e32 v18, v0
	v_mov_b32_e32 v19, v0
	v_mov_b32_e32 v20, v0
	v_mov_b32_e32 v21, v0
	v_mov_b32_e32 v22, v0
	v_mov_b32_e32 v23, v0
	v_mov_b32_e32 v32, v0
	v_mov_b32_e32 v33, v0
	v_mov_b32_e32 v34, v0
	v_mov_b32_e32 v35, v0
	v_mov_b32_e32 v36, v0
	v_mov_b32_e32 v37, v0
	v_mov_b32_e32 v38, v0
	v_mov_b32_e32 v39, v0
	v_mov_b32_e32 v48, v0
	v_mov_b32_e32 v49, v0
	v_mov_b32_e32 v50, v0
	v_mov_b32_e32 v51, v0
	v_mov_b32_e32 v52, v0
	v_mov_b32_e32 v53, v0
	v_mov_b32_e32 v54, v0
	v_mov_b32_e32 v55, v0
	v_mov_b32_e32 v8, v0
	v_mov_b32_e32 v9, v0
	v_mov_b32_e32 v10, v0
	v_mov_b32_e32 v11, v0
	v_mov_b32_e32 v12, v0
	v_mov_b32_e32 v13, v0
	v_mov_b32_e32 v14, v0
	v_mov_b32_e32 v15, v0
	v_mov_b32_e32 v24, v0
	v_mov_b32_e32 v25, v0
	v_mov_b32_e32 v26, v0
	v_mov_b32_e32 v27, v0
	v_mov_b32_e32 v28, v0
	v_mov_b32_e32 v29, v0
	v_mov_b32_e32 v30, v0
	v_mov_b32_e32 v31, v0
	v_mov_b32_e32 v40, v0
	v_mov_b32_e32 v41, v0
	v_mov_b32_e32 v42, v0
	v_mov_b32_e32 v43, v0
	v_mov_b32_e32 v44, v0
	v_mov_b32_e32 v45, v0
	v_mov_b32_e32 v46, v0
	v_mov_b32_e32 v47, v0
	v_mov_b32_e32 v56, v0
	v_mov_b32_e32 v57, v0
	v_mov_b32_e32 v58, v0
	v_mov_b32_e32 v59, v0
	v_mov_b32_e32 v60, v0
	v_mov_b32_e32 v61, v0
	v_mov_b32_e32 v62, v0
	v_mov_b32_e32 v63, v0
	v_mov_b32_e32 v64, v0
	v_mov_b32_e32 v65, v0
	v_mov_b32_e32 v66, v0
	v_mov_b32_e32 v67, v0
	v_mov_b32_e32 v68, v0
	v_mov_b32_e32 v69, v0
	v_mov_b32_e32 v70, v0
	v_mov_b32_e32 v71, v0
	v_mov_b32_e32 v80, v0
	v_mov_b32_e32 v81, v0
	v_mov_b32_e32 v82, v0
	v_mov_b32_e32 v83, v0
	v_mov_b32_e32 v84, v0
	v_mov_b32_e32 v85, v0
	v_mov_b32_e32 v86, v0
	v_mov_b32_e32 v87, v0
	v_mov_b32_e32 v96, v0
	v_mov_b32_e32 v97, v0
	v_mov_b32_e32 v98, v0
	v_mov_b32_e32 v99, v0
	v_mov_b32_e32 v100, v0
	v_mov_b32_e32 v101, v0
	v_mov_b32_e32 v102, v0
	v_mov_b32_e32 v103, v0
	v_mov_b32_e32 v112, v0
	v_mov_b32_e32 v113, v0
	v_mov_b32_e32 v114, v0
	v_mov_b32_e32 v115, v0
	v_mov_b32_e32 v116, v0
	v_mov_b32_e32 v117, v0
	v_mov_b32_e32 v118, v0
	v_mov_b32_e32 v119, v0
	v_mov_b32_e32 v72, v0
	v_mov_b32_e32 v73, v0
	v_mov_b32_e32 v74, v0
	v_mov_b32_e32 v75, v0
	v_mov_b32_e32 v76, v0
	v_mov_b32_e32 v77, v0
	v_mov_b32_e32 v78, v0
	v_mov_b32_e32 v79, v0
	v_mov_b32_e32 v88, v0
	v_mov_b32_e32 v89, v0
	v_mov_b32_e32 v90, v0
	v_mov_b32_e32 v91, v0
	v_mov_b32_e32 v92, v0
	v_mov_b32_e32 v93, v0
	v_mov_b32_e32 v94, v0
	v_mov_b32_e32 v95, v0
	v_mov_b32_e32 v104, v0
	v_mov_b32_e32 v105, v0
	v_mov_b32_e32 v106, v0
	v_mov_b32_e32 v107, v0
	v_mov_b32_e32 v108, v0
	v_mov_b32_e32 v109, v0
	v_mov_b32_e32 v110, v0
	v_mov_b32_e32 v111, v0
	v_mov_b32_e32 v120, v0
	v_mov_b32_e32 v121, v0
	v_mov_b32_e32 v122, v0
	v_mov_b32_e32 v123, v0
	v_mov_b32_e32 v124, v0
	v_mov_b32_e32 v125, v0
	v_mov_b32_e32 v126, v0
	v_mov_b32_e32 v127, v0

; template <class Epi, class Sched, bool ALIGN_EPI = false, bool SP2 = false>
; __device__ __forceinline__ void gemm_phase(PG8_LAS unsigned char* lds, const Gemm g, const Sched& S, const Epi& E) {
;     ...
;     f32x4 acc[2][2][4][2];
; #pragma unroll
;     for (int a = 0; a < 2; ++a)
; #pragma unroll
;         for (int b = 0; b < 2; ++b)
; #pragma unroll
;             for (int m = 0; m < 4; ++m)
; #pragma unroll
;                 for (int n = 0; n < 2; ++n) acc[a][b][m][n] = (f32x4){0.f, 0.f, 0.f, 0.f};
;     ...
;     for (;;) {
;         const bool has_next = S.next(ui + 1, nxt);
;         const char* nA = has_next ? (const char*)g.A + (size_t)nxt.pm * tstepA : cA; const char* nB = has_next ? (const char*)g.Bt + (size_t)nxt.pn * tstep : cB;
;         for (int t = 0; t < nt; t += 2) {
;             const bool last = (t == nt - 2);
;             const char* a1 = cA + (size_t)(t + 1) * kstep;
;             const char* a2 = last ? nA : cA + (size_t)(t + 2) * kstep; const char* b2 = last ? nB : cB + (size_t)(t + 2) * kstep;
;             const char* a3 = a2 + kstep; const char* b3 = b2 + kstep;
.LBB0_1047:
	v_mov_b32_e32 v123, 0
	s_andn2_b64 vcc, exec, s[72:73]
	v_mov_b32_e32 v122, v123
	v_mov_b32_e32 v121, v123
	v_mov_b32_e32 v120, v123
	v_mov_b32_e32 v127, v123
	v_mov_b32_e32 v126, v123
	v_mov_b32_e32 v125, v123
	v_mov_b32_e32 v124, v123
	v_mov_b32_e32 v111, v123
	v_mov_b32_e32 v110, v123
	v_mov_b32_e32 v109, v123
	v_mov_b32_e32 v108, v123
	v_mov_b32_e32 v107, v123
	v_mov_b32_e32 v106, v123
	v_mov_b32_e32 v105, v123
	v_mov_b32_e32 v104, v123
	v_mov_b32_e32 v95, v123
	v_mov_b32_e32 v94, v123
	v_mov_b32_e32 v93, v123
	v_mov_b32_e32 v92, v123
	v_mov_b32_e32 v91, v123
	v_mov_b32_e32 v90, v123
	v_mov_b32_e32 v89, v123
	v_mov_b32_e32 v88, v123
	v_mov_b32_e32 v79, v123
	v_mov_b32_e32 v78, v123
	v_mov_b32_e32 v77, v123
	v_mov_b32_e32 v76, v123
	v_mov_b32_e32 v75, v123
	v_mov_b32_e32 v74, v123
	v_mov_b32_e32 v73, v123
	v_mov_b32_e32 v72, v123
	v_mov_b32_e32 v119, v123
	v_mov_b32_e32 v118, v123
	v_mov_b32_e32 v117, v123
	v_mov_b32_e32 v116, v123
	v_mov_b32_e32 v115, v123
	v_mov_b32_e32 v114, v123
	v_mov_b32_e32 v113, v123
	v_mov_b32_e32 v112, v123
	v_mov_b32_e32 v103, v123
	v_mov_b32_e32 v102, v123
	v_mov_b32_e32 v101, v123
	v_mov_b32_e32 v100, v123
	v_mov_b32_e32 v99, v123
	v_mov_b32_e32 v98, v123
	v_mov_b32_e32 v97, v123
	v_mov_b32_e32 v96, v123
	v_mov_b32_e32 v87, v123
	v_mov_b32_e32 v86, v123
	v_mov_b32_e32 v85, v123
	v_mov_b32_e32 v84, v123
	v_mov_b32_e32 v83, v123
	v_mov_b32_e32 v82, v123
	v_mov_b32_e32 v81, v123
	v_mov_b32_e32 v80, v123
	v_mov_b32_e32 v71, v123
	v_mov_b32_e32 v70, v123
	v_mov_b32_e32 v69, v123
	v_mov_b32_e32 v68, v123
	v_mov_b32_e32 v67, v123
	v_mov_b32_e32 v66, v123
	v_mov_b32_e32 v65, v123
	v_mov_b32_e32 v64, v123
	v_mov_b32_e32 v63, v123
	v_mov_b32_e32 v62, v123
	v_mov_b32_e32 v61, v123
	v_mov_b32_e32 v60, v123
	v_mov_b32_e32 v59, v123
	v_mov_b32_e32 v58, v123
	v_mov_b32_e32 v57, v123
	v_mov_b32_e32 v56, v123
	v_mov_b32_e32 v47, v123
	v_mov_b32_e32 v46, v123
	v_mov_b32_e32 v45, v123
	v_mov_b32_e32 v44, v123
	v_mov_b32_e32 v43, v123
	v_mov_b32_e32 v42, v123
	v_mov_b32_e32 v41, v123
	v_mov_b32_e32 v40, v123
	v_mov_b32_e32 v31, v123
	v_mov_b32_e32 v30, v123
	v_mov_b32_e32 v29, v123
	v_mov_b32_e32 v28, v123
	v_mov_b32_e32 v27, v123
	v_mov_b32_e32 v26, v123
	v_mov_b32_e32 v25, v123
	v_mov_b32_e32 v24, v123
	v_mov_b32_e32 v15, v123
	v_mov_b32_e32 v14, v123
	v_mov_b32_e32 v13, v123
	v_mov_b32_e32 v12, v123
	v_mov_b32_e32 v11, v123
	v_mov_b32_e32 v10, v123
	v_mov_b32_e32 v9, v123
	v_mov_b32_e32 v8, v123
	v_mov_b32_e32 v55, v123
	v_mov_b32_e32 v54, v123
	v_mov_b32_e32 v53, v123
	v_mov_b32_e32 v52, v123
	v_mov_b32_e32 v51, v123
	v_mov_b32_e32 v50, v123
	v_mov_b32_e32 v49, v123
	v_mov_b32_e32 v48, v123
	v_mov_b32_e32 v39, v123
	v_mov_b32_e32 v38, v123
	v_mov_b32_e32 v37, v123
	v_mov_b32_e32 v36, v123
	v_mov_b32_e32 v35, v123
	v_mov_b32_e32 v34, v123
	v_mov_b32_e32 v33, v123
	v_mov_b32_e32 v32, v123
	v_mov_b32_e32 v23, v123
	v_mov_b32_e32 v22, v123
	v_mov_b32_e32 v21, v123
	v_mov_b32_e32 v20, v123
	v_mov_b32_e32 v19, v123
	v_mov_b32_e32 v18, v123
	v_mov_b32_e32 v17, v123
	v_mov_b32_e32 v16, v123
	v_mov_b32_e32 v7, v123
	v_mov_b32_e32 v6, v123
	v_mov_b32_e32 v5, v123
	v_mov_b32_e32 v4, v123
	v_mov_b32_e32 v3, v123
	v_mov_b32_e32 v2, v123
	v_mov_b32_e32 v1, v123
	v_mov_b32_e32 v0, v123
	s_cbranch_vccnz .LBB0_1050
	s_add_u32 s42, s42, 0x80
	s_addc_u32 s43, s43, 0
	s_add_u32 s57, s44, 0x100
	v_mov_b32_e32 v0, 0
	s_addc_u32 s58, s45, 0
	s_mov_b32 s44, 0
	v_mov_b32_e32 v1, v0
	v_mov_b32_e32 v2, v0
	v_mov_b32_e32 v3, v0
	v_mov_b32_e32 v4, v0
	v_mov_b32_e32 v5, v0
	v_mov_b32_e32 v6, v0
	v_mov_b32_e32 v7, v0
	v_mov_b32_e32 v16, v0
	v_mov_b32_e32 v17, v0
	v_mov_b32_e32 v18, v0
	v_mov_b32_e32 v19, v0
	v_mov_b32_e32 v20, v0
	v_mov_b32_e32 v21, v0
	v_mov_b32_e32 v22, v0
	v_mov_b32_e32 v23, v0
	v_mov_b32_e32 v32, v0
	v_mov_b32_e32 v33, v0
	v_mov_b32_e32 v34, v0
	v_mov_b32_e32 v35, v0
	v_mov_b32_e32 v36, v0
	v_mov_b32_e32 v37, v0
	v_mov_b32_e32 v38, v0
	v_mov_b32_e32 v39, v0
	v_mov_b32_e32 v48, v0
	v_mov_b32_e32 v49, v0
	v_mov_b32_e32 v50, v0
	v_mov_b32_e32 v51, v0
	v_mov_b32_e32 v52, v0
	v_mov_b32_e32 v53, v0
	v_mov_b32_e32 v54, v0
	v_mov_b32_e32 v55, v0
	v_mov_b32_e32 v8, v0
	v_mov_b32_e32 v9, v0
	v_mov_b32_e32 v10, v0
	v_mov_b32_e32 v11, v0
	v_mov_b32_e32 v12, v0
	v_mov_b32_e32 v13, v0
	v_mov_b32_e32 v14, v0
	v_mov_b32_e32 v15, v0
	v_mov_b32_e32 v24, v0
	v_mov_b32_e32 v25, v0
	v_mov_b32_e32 v26, v0
	v_mov_b32_e32 v27, v0
	v_mov_b32_e32 v28, v0
	v_mov_b32_e32 v29, v0
	v_mov_b32_e32 v30, v0
	v_mov_b32_e32 v31, v0
	v_mov_b32_e32 v40, v0
	v_mov_b32_e32 v41, v0
	v_mov_b32_e32 v42, v0
	v_mov_b32_e32 v43, v0
	v_mov_b32_e32 v44, v0
	v_mov_b32_e32 v45, v0
	v_mov_b32_e32 v46, v0
	v_mov_b32_e32 v47, v0
	v_mov_b32_e32 v56, v0
	v_mov_b32_e32 v57, v0
	v_mov_b32_e32 v58, v0
	v_mov_b32_e32 v59, v0
	v_mov_b32_e32 v60, v0
	v_mov_b32_e32 v61, v0
	v_mov_b32_e32 v62, v0
	v_mov_b32_e32 v63, v0
	v_mov_b32_e32 v64, v0
	v_mov_b32_e32 v65, v0
	v_mov_b32_e32 v66, v0
	v_mov_b32_e32 v67, v0
	v_mov_b32_e32 v68, v0
	v_mov_b32_e32 v69, v0
	v_mov_b32_e32 v70, v0
	v_mov_b32_e32 v71, v0
	v_mov_b32_e32 v80, v0
	v_mov_b32_e32 v81, v0
	v_mov_b32_e32 v82, v0
	v_mov_b32_e32 v83, v0
	v_mov_b32_e32 v84, v0
	v_mov_b32_e32 v85, v0
	v_mov_b32_e32 v86, v0
	v_mov_b32_e32 v87, v0
	v_mov_b32_e32 v96, v0
	v_mov_b32_e32 v97, v0
	v_mov_b32_e32 v98, v0
	v_mov_b32_e32 v99, v0
	v_mov_b32_e32 v100, v0
	v_mov_b32_e32 v101, v0
	v_mov_b32_e32 v102, v0
	v_mov_b32_e32 v103, v0
	v_mov_b32_e32 v112, v0
	v_mov_b32_e32 v113, v0
	v_mov_b32_e32 v114, v0
	v_mov_b32_e32 v115, v0
	v_mov_b32_e32 v116, v0
	v_mov_b32_e32 v117, v0
	v_mov_b32_e32 v118, v0
	v_mov_b32_e32 v119, v0
	v_mov_b32_e32 v72, v0
	v_mov_b32_e32 v73, v0
	v_mov_b32_e32 v74, v0
	v_mov_b32_e32 v75, v0
	v_mov_b32_e32 v76, v0
	v_mov_b32_e32 v77, v0
	v_mov_b32_e32 v78, v0
	v_mov_b32_e32 v79, v0
	v_mov_b32_e32 v88, v0
	v_mov_b32_e32 v89, v0
	v_mov_b32_e32 v90, v0
	v_mov_b32_e32 v91, v0
	v_mov_b32_e32 v92, v0
	v_mov_b32_e32 v93, v0
	v_mov_b32_e32 v94, v0
	v_mov_b32_e32 v95, v0
	v_mov_b32_e32 v104, v0
	v_mov_b32_e32 v105, v0
	v_mov_b32_e32 v106, v0
	v_mov_b32_e32 v107, v0
	v_mov_b32_e32 v108, v0
	v_mov_b32_e32 v109, v0
	v_mov_b32_e32 v110, v0
	v_mov_b32_e32 v111, v0
	v_mov_b32_e32 v124, v0
	v_mov_b32_e32 v125, v0
	v_mov_b32_e32 v126, v0
	v_mov_b32_e32 v127, v0
	v_mov_b32_e32 v120, v0
	v_mov_b32_e32 v121, v0
	v_mov_b32_e32 v122, v0
	v_mov_b32_e32 v123, v0

; template <class Epi, class Sched, bool ALIGN_EPI = false, bool SP2 = false>
; __device__ __forceinline__ void gemm_phase(PG8_LAS unsigned char* lds, const Gemm g, const Sched& S, const Epi& E) {
;     ...
;     f32x4 acc[2][2][4][2];
; #pragma unroll
;     for (int a = 0; a < 2; ++a)
; #pragma unroll
;         for (int b = 0; b < 2; ++b)
; #pragma unroll
;             for (int m = 0; m < 4; ++m)
; #pragma unroll
;                 for (int n = 0; n < 2; ++n) acc[a][b][m][n] = (f32x4){0.f, 0.f, 0.f, 0.f};
;     ...
;     for (;;) {
;         const bool has_next = S.next(ui + 1, nxt);
;         const char* nA = has_next ? (const char*)g.A + (size_t)nxt.pm * tstepA : cA; const char* nB = has_next ? (const char*)g.Bt + (size_t)nxt.pn * tstep : cB;
;         for (int t = 0; t < nt; t += 2) {
;             const bool last = (t == nt - 2);
;             const char* a1 = cA + (size_t)(t + 1) * kstep;
;             const char* a2 = last ? nA : cA + (size_t)(t + 2) * kstep; const char* b2 = last ? nB : cB + (size_t)(t + 2) * kstep;
;             const char* a3 = a2 + kstep; const char* b3 = b2 + kstep;
.LBB0_1166:
	v_mov_b32_e32 v123, 0
	s_andn2_b64 vcc, exec, s[72:73]
	v_mov_b32_e32 v122, v123
	v_mov_b32_e32 v121, v123
	v_mov_b32_e32 v120, v123
	v_mov_b32_e32 v115, v123
	v_mov_b32_e32 v114, v123
	v_mov_b32_e32 v113, v123
	v_mov_b32_e32 v112, v123
	v_mov_b32_e32 v107, v123
	v_mov_b32_e32 v106, v123
	v_mov_b32_e32 v105, v123
	v_mov_b32_e32 v104, v123
	v_mov_b32_e32 v99, v123
	v_mov_b32_e32 v98, v123
	v_mov_b32_e32 v97, v123
	v_mov_b32_e32 v96, v123
	v_mov_b32_e32 v91, v123
	v_mov_b32_e32 v90, v123
	v_mov_b32_e32 v89, v123
	v_mov_b32_e32 v88, v123
	v_mov_b32_e32 v83, v123
	v_mov_b32_e32 v82, v123
	v_mov_b32_e32 v81, v123
	v_mov_b32_e32 v80, v123
	v_mov_b32_e32 v75, v123
	v_mov_b32_e32 v74, v123
	v_mov_b32_e32 v73, v123
	v_mov_b32_e32 v72, v123
	v_mov_b32_e32 v67, v123
	v_mov_b32_e32 v66, v123
	v_mov_b32_e32 v65, v123
	v_mov_b32_e32 v64, v123
	v_mov_b32_e32 v127, v123
	v_mov_b32_e32 v126, v123
	v_mov_b32_e32 v125, v123
	v_mov_b32_e32 v124, v123
	v_mov_b32_e32 v119, v123
	v_mov_b32_e32 v118, v123
	v_mov_b32_e32 v117, v123
	v_mov_b32_e32 v116, v123
	v_mov_b32_e32 v111, v123
	v_mov_b32_e32 v110, v123
	v_mov_b32_e32 v109, v123
	v_mov_b32_e32 v108, v123
	v_mov_b32_e32 v103, v123
	v_mov_b32_e32 v102, v123
	v_mov_b32_e32 v101, v123
	v_mov_b32_e32 v100, v123
	v_mov_b32_e32 v95, v123
	v_mov_b32_e32 v94, v123
	v_mov_b32_e32 v93, v123
	v_mov_b32_e32 v92, v123
	v_mov_b32_e32 v87, v123
	v_mov_b32_e32 v86, v123
	v_mov_b32_e32 v85, v123
	v_mov_b32_e32 v84, v123
	v_mov_b32_e32 v79, v123
	v_mov_b32_e32 v78, v123
	v_mov_b32_e32 v77, v123
	v_mov_b32_e32 v76, v123
	v_mov_b32_e32 v71, v123
	v_mov_b32_e32 v70, v123
	v_mov_b32_e32 v69, v123
	v_mov_b32_e32 v68, v123
	v_mov_b32_e32 v59, v123
	v_mov_b32_e32 v58, v123
	v_mov_b32_e32 v57, v123
	v_mov_b32_e32 v56, v123
	v_mov_b32_e32 v51, v123
	v_mov_b32_e32 v50, v123
	v_mov_b32_e32 v49, v123
	v_mov_b32_e32 v48, v123
	v_mov_b32_e32 v43, v123
	v_mov_b32_e32 v42, v123
	v_mov_b32_e32 v41, v123
	v_mov_b32_e32 v40, v123
	v_mov_b32_e32 v35, v123
	v_mov_b32_e32 v34, v123
	v_mov_b32_e32 v33, v123
	v_mov_b32_e32 v32, v123
	v_mov_b32_e32 v27, v123
	v_mov_b32_e32 v26, v123
	v_mov_b32_e32 v25, v123
	v_mov_b32_e32 v24, v123
	v_mov_b32_e32 v19, v123
	v_mov_b32_e32 v18, v123
	v_mov_b32_e32 v17, v123
	v_mov_b32_e32 v16, v123
	v_mov_b32_e32 v11, v123
	v_mov_b32_e32 v10, v123
	v_mov_b32_e32 v9, v123
	v_mov_b32_e32 v8, v123
	v_mov_b32_e32 v7, v123
	v_mov_b32_e32 v6, v123
	v_mov_b32_e32 v5, v123
	v_mov_b32_e32 v4, v123
	v_mov_b32_e32 v63, v123
	v_mov_b32_e32 v62, v123
	v_mov_b32_e32 v61, v123
	v_mov_b32_e32 v60, v123
	v_mov_b32_e32 v55, v123
	v_mov_b32_e32 v54, v123
	v_mov_b32_e32 v53, v123
	v_mov_b32_e32 v52, v123
	v_mov_b32_e32 v47, v123
	v_mov_b32_e32 v46, v123
	v_mov_b32_e32 v45, v123
	v_mov_b32_e32 v44, v123
	v_mov_b32_e32 v39, v123
	v_mov_b32_e32 v38, v123
	v_mov_b32_e32 v37, v123
	v_mov_b32_e32 v36, v123
	v_mov_b32_e32 v31, v123
	v_mov_b32_e32 v30, v123
	v_mov_b32_e32 v29, v123
	v_mov_b32_e32 v28, v123
	v_mov_b32_e32 v23, v123
	v_mov_b32_e32 v22, v123
	v_mov_b32_e32 v21, v123
	v_mov_b32_e32 v20, v123
	v_mov_b32_e32 v15, v123
	v_mov_b32_e32 v14, v123
	v_mov_b32_e32 v13, v123
	v_mov_b32_e32 v12, v123
	v_mov_b32_e32 v3, v123
	v_mov_b32_e32 v2, v123
	v_mov_b32_e32 v1, v123
	v_mov_b32_e32 v0, v123
	s_cbranch_vccnz .LBB0_1169
	s_add_u32 s4, s4, 0x80
	s_addc_u32 s5, s5, 0
	s_add_u32 s20, s22, 0x100
	v_mov_b32_e32 v0, 0
	s_addc_u32 s21, s23, 0
	s_mov_b32 s22, 0
	v_mov_b32_e32 v1, v0
	v_mov_b32_e32 v2, v0
	v_mov_b32_e32 v3, v0
	v_mov_b32_e32 v12, v0
	v_mov_b32_e32 v13, v0
	v_mov_b32_e32 v14, v0
	v_mov_b32_e32 v15, v0
	v_mov_b32_e32 v20, v0
	v_mov_b32_e32 v21, v0
	v_mov_b32_e32 v22, v0
	v_mov_b32_e32 v23, v0
	v_mov_b32_e32 v28, v0
	v_mov_b32_e32 v29, v0
	v_mov_b32_e32 v30, v0
	v_mov_b32_e32 v31, v0
	v_mov_b32_e32 v36, v0
	v_mov_b32_e32 v37, v0
	v_mov_b32_e32 v38, v0
	v_mov_b32_e32 v39, v0
	v_mov_b32_e32 v44, v0
	v_mov_b32_e32 v45, v0
	v_mov_b32_e32 v46, v0
	v_mov_b32_e32 v47, v0
	v_mov_b32_e32 v52, v0
	v_mov_b32_e32 v53, v0
	v_mov_b32_e32 v54, v0
	v_mov_b32_e32 v55, v0
	v_mov_b32_e32 v60, v0
	v_mov_b32_e32 v61, v0
	v_mov_b32_e32 v62, v0
	v_mov_b32_e32 v63, v0
	v_mov_b32_e32 v4, v0
	v_mov_b32_e32 v5, v0
	v_mov_b32_e32 v6, v0
	v_mov_b32_e32 v7, v0
	v_mov_b32_e32 v8, v0
	v_mov_b32_e32 v9, v0
	v_mov_b32_e32 v10, v0
	v_mov_b32_e32 v11, v0
	v_mov_b32_e32 v16, v0
	v_mov_b32_e32 v17, v0
	v_mov_b32_e32 v18, v0
	v_mov_b32_e32 v19, v0
	v_mov_b32_e32 v24, v0
	v_mov_b32_e32 v25, v0
	v_mov_b32_e32 v26, v0
	v_mov_b32_e32 v27, v0
	v_mov_b32_e32 v32, v0
	v_mov_b32_e32 v33, v0
	v_mov_b32_e32 v34, v0
	v_mov_b32_e32 v35, v0
	v_mov_b32_e32 v40, v0
	v_mov_b32_e32 v41, v0
	v_mov_b32_e32 v42, v0
	v_mov_b32_e32 v43, v0
	v_mov_b32_e32 v48, v0
	v_mov_b32_e32 v49, v0
	v_mov_b32_e32 v50, v0
	v_mov_b32_e32 v51, v0
	v_mov_b32_e32 v56, v0
	v_mov_b32_e32 v57, v0
	v_mov_b32_e32 v58, v0
	v_mov_b32_e32 v59, v0
	v_mov_b32_e32 v68, v0
	v_mov_b32_e32 v69, v0
	v_mov_b32_e32 v70, v0
	v_mov_b32_e32 v71, v0
	v_mov_b32_e32 v76, v0
	v_mov_b32_e32 v77, v0
	v_mov_b32_e32 v78, v0
	v_mov_b32_e32 v79, v0
	v_mov_b32_e32 v84, v0
	v_mov_b32_e32 v85, v0
	v_mov_b32_e32 v86, v0
	v_mov_b32_e32 v87, v0
	v_mov_b32_e32 v92, v0
	v_mov_b32_e32 v93, v0
	v_mov_b32_e32 v94, v0
	v_mov_b32_e32 v95, v0
	v_mov_b32_e32 v100, v0
	v_mov_b32_e32 v101, v0
	v_mov_b32_e32 v102, v0
	v_mov_b32_e32 v103, v0
	v_mov_b32_e32 v108, v0
	v_mov_b32_e32 v109, v0
	v_mov_b32_e32 v110, v0
	v_mov_b32_e32 v111, v0
	v_mov_b32_e32 v116, v0
	v_mov_b32_e32 v117, v0
	v_mov_b32_e32 v118, v0
	v_mov_b32_e32 v119, v0
	v_mov_b32_e32 v124, v0
	v_mov_b32_e32 v125, v0
	v_mov_b32_e32 v126, v0
	v_mov_b32_e32 v127, v0
	v_mov_b32_e32 v64, v0
	v_mov_b32_e32 v65, v0
	v_mov_b32_e32 v66, v0
	v_mov_b32_e32 v67, v0
	v_mov_b32_e32 v72, v0
	v_mov_b32_e32 v73, v0
	v_mov_b32_e32 v74, v0
	v_mov_b32_e32 v75, v0
	v_mov_b32_e32 v80, v0
	v_mov_b32_e32 v81, v0
	v_mov_b32_e32 v82, v0
	v_mov_b32_e32 v83, v0
	v_mov_b32_e32 v88, v0
	v_mov_b32_e32 v89, v0
	v_mov_b32_e32 v90, v0
	v_mov_b32_e32 v91, v0
	v_mov_b32_e32 v96, v0
	v_mov_b32_e32 v97, v0
	v_mov_b32_e32 v98, v0
	v_mov_b32_e32 v99, v0
	v_mov_b32_e32 v104, v0
	v_mov_b32_e32 v105, v0
	v_mov_b32_e32 v106, v0
	v_mov_b32_e32 v107, v0
	v_mov_b32_e32 v112, v0
	v_mov_b32_e32 v113, v0
	v_mov_b32_e32 v114, v0
	v_mov_b32_e32 v115, v0
	v_mov_b32_e32 v120, v0
	v_mov_b32_e32 v121, v0
	v_mov_b32_e32 v122, v0
	v_mov_b32_e32 v123, v0
